# LayerNorm-2 half-wave sums via DPP row reductions + readlane instead of 2x5 ds_bpermute levels
# speedup vs baseline: 1.0072x; 1.0072x over previous
.Lg_noex:
	global_load_dwordx4 v[0:3], v[124:125], off offset:48
	global_load_dwordx4 v[8:11], v[124:125], off offset:32
	global_load_dwordx4 v[20:23], v[124:125], off offset:16
	global_load_dwordx4 v[32:35], v[124:125], off
	global_load_dwordx4 v[12:15], v[126:127], off offset:48
	global_load_dwordx4 v[28:31], v[126:127], off offset:32
	global_load_dwordx4 v[40:43], v[126:127], off offset:16
	global_load_dwordx4 v[52:55], v[126:127], off
	global_load_dwordx4 v[4:7], v[124:125], off offset:112
	global_load_dwordx4 v[24:27], v[124:125], off offset:96
	global_load_dwordx4 v[36:39], v[124:125], off offset:80
	global_load_dwordx4 v[48:51], v[124:125], off offset:64
	global_load_dwordx4 v[16:19], v[126:127], off offset:112
	global_load_dwordx4 v[44:47], v[126:127], off offset:96
	ds_bpermute_b32 v88, v243, v56
	ds_bpermute_b32 v89, v243, v60
	ds_bpermute_b32 v92, v243, v57
	ds_bpermute_b32 v93, v243, v61
	v_mov_b32_e32 v178, v56
	v_mov_b32_e32 v179, v60
	s_waitcnt lgkmcnt(2)
	v_pk_add_f32 v[88:89], v[178:179], v[88:89]
	s_mov_b32 s2, 0x3fd744fd
	v_mov_b32_e32 v60, v57
	ds_bpermute_b32 v94, v243, v58
	ds_bpermute_b32 v95, v243, v64
	v_pk_fma_f32 v[88:89], v[152:153], s[2:3], v[88:89] op_sel_hi:[1,0,1]
	s_waitcnt lgkmcnt(2)
	v_pk_add_f32 v[56:57], v[60:61], v[92:93]
	ds_bpermute_b32 v96, v243, v59
	ds_bpermute_b32 v97, v243, v65
	v_add_f32_e32 v117, 0, v88
	v_pk_fma_f32 v[92:93], v[150:151], s[2:3], v[56:57] op_sel_hi:[1,0,1]
	v_mov_b32_e32 v57, v64
	v_add_f32_e32 v56, v117, v92
	v_add_f32_e32 v56, v56, v89
	v_add_f32_e32 v60, v56, v93
	v_mov_b32_e32 v56, v58
	s_waitcnt lgkmcnt(2)
	v_pk_add_f32 v[56:57], v[56:57], v[94:95]
	v_mov_b32_e32 v64, v59
	ds_bpermute_b32 v98, v243, v62
	ds_bpermute_b32 v99, v243, v68
	v_pk_fma_f32 v[94:95], v[148:149], s[2:3], v[56:57] op_sel_hi:[1,0,1]
	s_waitcnt lgkmcnt(2)
	v_pk_add_f32 v[56:57], v[64:65], v[96:97]
	ds_bpermute_b32 v100, v243, v63
	ds_bpermute_b32 v101, v243, v69
	v_pk_fma_f32 v[64:65], v[146:147], s[2:3], v[56:57] op_sel_hi:[1,0,1]
	v_add_f32_e32 v56, v60, v94
	v_add_f32_e32 v56, v56, v64
	v_add_f32_e32 v56, v56, v95
	v_add_f32_e32 v58, v56, v65
	v_mov_b32_e32 v56, v62
	v_mov_b32_e32 v57, v68
	s_waitcnt lgkmcnt(2)
	v_pk_add_f32 v[56:57], v[56:57], v[98:99]
	v_mov_b32_e32 v68, v63
	ds_bpermute_b32 v102, v243, v66
	ds_bpermute_b32 v103, v243, v72
	v_pk_fma_f32 v[96:97], v[144:145], s[2:3], v[56:57] op_sel_hi:[1,0,1]
	s_waitcnt lgkmcnt(2)
	v_pk_add_f32 v[56:57], v[68:69], v[100:101]
	ds_bpermute_b32 v104, v243, v67
	ds_bpermute_b32 v105, v243, v73
	v_pk_fma_f32 v[68:69], v[142:143], s[2:3], v[56:57] op_sel_hi:[1,0,1]
	v_add_f32_e32 v56, v58, v96
	v_add_f32_e32 v56, v56, v68
	v_add_f32_e32 v56, v56, v97
	v_add_f32_e32 v58, v56, v69
	v_mov_b32_e32 v56, v66
	v_mov_b32_e32 v57, v72
	s_waitcnt lgkmcnt(2)
	v_pk_add_f32 v[56:57], v[56:57], v[102:103]
	v_mov_b32_e32 v72, v67
	ds_bpermute_b32 v106, v243, v70
	ds_bpermute_b32 v107, v243, v76
	v_pk_fma_f32 v[98:99], v[140:141], s[2:3], v[56:57] op_sel_hi:[1,0,1]
	s_waitcnt lgkmcnt(2)
	v_pk_add_f32 v[56:57], v[72:73], v[104:105]
	ds_bpermute_b32 v108, v243, v71
	ds_bpermute_b32 v109, v243, v77
	v_pk_fma_f32 v[66:67], v[138:139], s[2:3], v[56:57] op_sel_hi:[1,0,1]
	v_add_f32_e32 v56, v58, v98
	v_add_f32_e32 v56, v56, v66
	v_add_f32_e32 v56, v56, v99
	v_add_f32_e32 v58, v56, v67
	v_mov_b32_e32 v56, v70
	v_mov_b32_e32 v57, v76
	s_waitcnt lgkmcnt(2)
	v_pk_add_f32 v[56:57], v[56:57], v[106:107]
	v_mov_b32_e32 v76, v71
	ds_bpermute_b32 v110, v243, v74
	ds_bpermute_b32 v111, v243, v82
	v_pk_fma_f32 v[72:73], v[168:169], s[2:3], v[56:57] op_sel_hi:[1,0,1]
	s_waitcnt lgkmcnt(2)
	v_pk_add_f32 v[56:57], v[76:77], v[108:109]
	ds_bpermute_b32 v112, v243, v75
	ds_bpermute_b32 v113, v243, v83
	v_pk_fma_f32 v[70:71], v[166:167], s[2:3], v[56:57] op_sel_hi:[1,0,1]
	v_add_f32_e32 v56, v58, v72
	v_add_f32_e32 v56, v56, v70
	v_add_f32_e32 v56, v56, v73
	v_add_f32_e32 v58, v56, v71
	v_mov_b32_e32 v56, v74
	v_mov_b32_e32 v57, v82
	s_waitcnt lgkmcnt(2)
	v_pk_add_f32 v[56:57], v[56:57], v[110:111]
	v_mov_b32_e32 v82, v75
	ds_bpermute_b32 v170, v243, v78
	ds_bpermute_b32 v171, v243, v90
	v_pk_fma_f32 v[76:77], v[164:165], s[2:3], v[56:57] op_sel_hi:[1,0,1]
	s_waitcnt lgkmcnt(2)
	v_pk_add_f32 v[56:57], v[82:83], v[112:113]
	ds_bpermute_b32 v172, v243, v79
	ds_bpermute_b32 v173, v243, v91
	v_pk_fma_f32 v[74:75], v[162:163], s[2:3], v[56:57] op_sel_hi:[1,0,1]
	v_add_f32_e32 v56, v58, v76
	v_add_f32_e32 v56, v56, v74
	v_add_f32_e32 v56, v56, v77
	v_add_f32_e32 v58, v56, v75
	v_mov_b32_e32 v56, v78
	v_mov_b32_e32 v57, v90
	s_waitcnt lgkmcnt(2)
	v_pk_add_f32 v[56:57], v[56:57], v[170:171]
	v_mov_b32_e32 v90, v79
	ds_bpermute_b32 v174, v243, v86
	ds_bpermute_b32 v175, v243, v84
	v_pk_fma_f32 v[82:83], v[160:161], s[2:3], v[56:57] op_sel_hi:[1,0,1]
	s_waitcnt lgkmcnt(2)
	v_pk_add_f32 v[56:57], v[90:91], v[172:173]
	ds_bpermute_b32 v176, v243, v87
	ds_bpermute_b32 v177, v243, v85
	v_pk_fma_f32 v[78:79], v[158:159], s[2:3], v[56:57] op_sel_hi:[1,0,1]
	v_add_f32_e32 v56, v58, v82
	v_add_f32_e32 v56, v56, v78
	v_add_f32_e32 v56, v56, v83
	v_add_f32_e32 v58, v56, v79
	v_mov_b32_e32 v56, v86
	v_mov_b32_e32 v57, v84
	s_waitcnt lgkmcnt(2)
	v_pk_add_f32 v[56:57], v[56:57], v[174:175]
	v_mov_b32_e32 v84, v87
	v_pk_fma_f32 v[90:91], v[156:157], s[2:3], v[56:57] op_sel_hi:[1,0,1]
	s_waitcnt lgkmcnt(0)
	v_pk_add_f32 v[56:57], v[84:85], v[176:177]
	s_waitcnt vmcnt(10)
	v_mov_b32_e32 v86, v32
	v_pk_fma_f32 v[84:85], v[154:155], s[2:3], v[56:57] op_sel_hi:[1,0,1]
	v_add_f32_e32 v56, v58, v90
	v_add_f32_e32 v56, v56, v84
	v_add_f32_e32 v56, v56, v91
	v_add_f32_e32 v101, v56, v85
	s_nop 1
	v_add_f32_dpp v254, v101, v101 quad_perm:[1,0,3,2] row_mask:0xf bank_mask:0xf
	s_nop 1
	v_add_f32_dpp v254, v254, v254 quad_perm:[2,3,0,1] row_mask:0xf bank_mask:0xf
	s_nop 1
	v_add_f32_dpp v254, v254, v254 row_half_mirror row_mask:0xf bank_mask:0xf
	s_nop 1
	v_add_f32_dpp v254, v254, v254 row_mirror row_mask:0xf bank_mask:0xf
	s_nop 1
	v_add_f32_dpp v254, v254, v254 row_bcast:15 row_mask:0xa bank_mask:0xf
	s_nop 1
	v_readlane_b32 s64, v254, 31
	s_waitcnt vmcnt(6)
	v_mov_b32_e32 v100, v52
	v_mov_b32_e32 v52, v20
	global_load_dwordx4 v[56:59], v[126:127], off offset:80
	global_load_dwordx4 v[60:63], v[126:127], off offset:64
	v_mov_b32_e32 v87, v34
	s_waitcnt lgkmcnt(0)
	v_mov_b32_e32 v34, v33
	v_mov_b32_e32 v103, v42
	v_mov_b32_e32 v42, v41
	v_mov_b32_e32 v41, v30
	s_waitcnt lgkmcnt(0)
	v_mov_b32_e32 v102, v40
	v_mov_b32_e32 v40, v28
	v_mov_b32_e32 v30, v29
	s_mov_b32 s2, 0x800000
	s_waitcnt lgkmcnt(0)
	v_mov_b32_e32 v20, v8
	v_mov_b32_e32 v8, v0
	v_mov_b32_e32 v101, v54
	v_mov_b32_e32 v54, v53
	s_waitcnt lgkmcnt(0)
	v_mov_b32_e32 v53, v22
	v_mov_b32_e32 v22, v21
	v_mov_b32_e32 v21, v10
	v_mov_b32_e32 v10, v9
	s_waitcnt lgkmcnt(0)
	s_nop 0
	v_mov_b32_e32 v0, s64
	v_mul_f32_e32 v0, 0x3a800000, v0
	v_pk_add_f32 v[28:29], v[88:89], v[0:1] op_sel_hi:[1,0] neg_lo:[0,1] neg_hi:[0,1]
	v_pk_add_f32 v[88:89], v[92:93], v[0:1] op_sel_hi:[1,0] neg_lo:[0,1] neg_hi:[0,1]
	v_pk_mul_f32 v[32:33], v[28:29], v[28:29]
	v_pk_mul_f32 v[92:93], v[88:89], v[88:89]
	v_pk_add_f32 v[94:95], v[94:95], v[0:1] op_sel_hi:[1,0] neg_lo:[0,1] neg_hi:[0,1]
	v_pk_add_f32 v[64:65], v[64:65], v[0:1] op_sel_hi:[1,0] neg_lo:[0,1] neg_hi:[0,1]
	v_pk_add_f32 v[96:97], v[96:97], v[0:1] op_sel_hi:[1,0] neg_lo:[0,1] neg_hi:[0,1]
	v_pk_add_f32 v[68:69], v[68:69], v[0:1] op_sel_hi:[1,0] neg_lo:[0,1] neg_hi:[0,1]
	v_pk_add_f32 v[98:99], v[98:99], v[0:1] op_sel_hi:[1,0] neg_lo:[0,1] neg_hi:[0,1]
	v_pk_add_f32 v[66:67], v[66:67], v[0:1] op_sel_hi:[1,0] neg_lo:[0,1] neg_hi:[0,1]
	v_pk_add_f32 v[72:73], v[72:73], v[0:1] op_sel_hi:[1,0] neg_lo:[0,1] neg_hi:[0,1]
	v_pk_add_f32 v[70:71], v[70:71], v[0:1] op_sel_hi:[1,0] neg_lo:[0,1] neg_hi:[0,1]
	v_pk_add_f32 v[76:77], v[76:77], v[0:1] op_sel_hi:[1,0] neg_lo:[0,1] neg_hi:[0,1]
	v_pk_add_f32 v[74:75], v[74:75], v[0:1] op_sel_hi:[1,0] neg_lo:[0,1] neg_hi:[0,1]
	v_pk_add_f32 v[82:83], v[82:83], v[0:1] op_sel_hi:[1,0] neg_lo:[0,1] neg_hi:[0,1]
	v_pk_add_f32 v[78:79], v[78:79], v[0:1] op_sel_hi:[1,0] neg_lo:[0,1] neg_hi:[0,1]
	v_pk_add_f32 v[90:91], v[90:91], v[0:1] op_sel_hi:[1,0] neg_lo:[0,1] neg_hi:[0,1]
	v_pk_add_f32 v[84:85], v[84:85], v[0:1] op_sel_hi:[1,0] neg_lo:[0,1] neg_hi:[0,1]
	v_add_f32_e32 v0, v32, v92
	v_add_f32_e32 v0, v33, v0
	v_pk_mul_f32 v[104:105], v[94:95], v[94:95]
	v_add_f32_e32 v0, v93, v0
	v_pk_mul_f32 v[106:107], v[64:65], v[64:65]
	v_add_f32_e32 v0, v104, v0
	v_add_f32_e32 v0, v106, v0
	v_add_f32_e32 v0, v105, v0
	v_pk_mul_f32 v[108:109], v[96:97], v[96:97]
	v_add_f32_e32 v0, v107, v0
	v_pk_mul_f32 v[110:111], v[68:69], v[68:69]
	v_add_f32_e32 v0, v108, v0
	v_add_f32_e32 v0, v110, v0
	v_add_f32_e32 v0, v109, v0
	v_pk_mul_f32 v[112:113], v[98:99], v[98:99]
	v_add_f32_e32 v0, v111, v0
	v_pk_mul_f32 v[138:139], v[66:67], v[66:67]
	v_add_f32_e32 v0, v112, v0
	v_add_f32_e32 v0, v138, v0
	v_add_f32_e32 v0, v113, v0
	v_pk_mul_f32 v[140:141], v[72:73], v[72:73]
	v_add_f32_e32 v0, v139, v0
	v_pk_mul_f32 v[142:143], v[70:71], v[70:71]
	v_add_f32_e32 v0, v140, v0
	v_add_f32_e32 v0, v142, v0
	v_add_f32_e32 v0, v141, v0
	v_pk_mul_f32 v[144:145], v[76:77], v[76:77]
	v_add_f32_e32 v0, v143, v0
	v_pk_mul_f32 v[146:147], v[74:75], v[74:75]
	v_add_f32_e32 v0, v144, v0
	v_add_f32_e32 v0, v146, v0
	v_add_f32_e32 v0, v145, v0
	v_add_f32_e32 v0, v147, v0
	v_mov_b32_e32 v148, v79
	v_mov_b32_e32 v149, v83
	v_fmac_f32_e32 v0, v82, v82
	v_pk_mul_f32 v[148:149], v[148:149], v[148:149]
	v_fmac_f32_e32 v0, v78, v78
	v_mov_b32_e32 v150, v84
	v_mov_b32_e32 v151, v90
	v_add_f32_e32 v0, v149, v0
	v_pk_mul_f32 v[150:151], v[150:151], v[150:151]
	v_add_f32_e32 v0, v148, v0
	v_mov_b32_e32 v152, v85
	v_mov_b32_e32 v153, v91
	v_add_f32_e32 v0, v151, v0
	v_pk_mul_f32 v[152:153], v[152:153], v[152:153]
	v_add_f32_e32 v0, v150, v0
	v_add_f32_e32 v0, v153, v0
	v_add_f32_e32 v0, v152, v0
	s_nop 1
	v_add_f32_dpp v254, v0, v0 quad_perm:[1,0,3,2] row_mask:0xf bank_mask:0xf
	s_nop 1
	v_add_f32_dpp v254, v254, v254 quad_perm:[2,3,0,1] row_mask:0xf bank_mask:0xf
	s_nop 1
	v_add_f32_dpp v254, v254, v254 row_half_mirror row_mask:0xf bank_mask:0xf
	s_nop 1
	v_add_f32_dpp v254, v254, v254 row_mirror row_mask:0xf bank_mask:0xf
	s_nop 1
	v_add_f32_dpp v254, v254, v254 row_bcast:15 row_mask:0xa bank_mask:0xf
	s_nop 1
	v_readlane_b32 s65, v254, 31
	s_waitcnt vmcnt(1)
	v_mov_b32_e32 v104, v56
	v_mov_b32_e32 v56, v24
	v_mov_b32_e32 v105, v58
	v_mov_b32_e32 v58, v57
	s_waitcnt lgkmcnt(0)
	v_mov_b32_e32 v57, v26
	v_mov_b32_e32 v106, v44
	v_mov_b32_e32 v107, v46
	v_mov_b32_e32 v46, v45
	s_waitcnt lgkmcnt(0)
	v_mov_b32_e32 v9, v2
	v_mov_b32_e32 v2, v1
	v_mov_b32_e32 v0, v48
	v_mov_b32_e32 v1, v50
	s_waitcnt lgkmcnt(0)
	v_mov_b32_e32 v50, v49
	v_mov_b32_e32 v92, v12
	v_mov_b32_e32 v93, v14
	v_mov_b32_e32 v14, v13
	s_waitcnt lgkmcnt(0)
	s_waitcnt vmcnt(0)
	v_mov_b32_e32 v12, v60
	v_mov_b32_e32 v13, v62
	v_mov_b32_e32 v62, v61
	v_mov_b32_e32 v60, v36
	s_waitcnt lgkmcnt(0)
	s_nop 0
	v_mov_b32_e32 v24, s65
	v_fmamk_f32 v24, v24, 0x3a800000, v221
	v_mul_f32_e32 v26, 0x4b800000, v24
	v_cmp_gt_f32_e32 vcc, s2, v24
	v_mov_b32_e32 v61, v38
	v_mov_b32_e32 v38, v37
	v_cndmask_b32_e32 v24, v24, v26, vcc
	v_rsq_f32_e32 v24, v24
	v_mov_b32_e32 v26, v25
	v_mul_f32_e32 v25, 0x45800000, v24
	v_cndmask_b32_e32 v108, v24, v25, vcc
	v_pk_mul_f32 v[24:25], v[28:29], v[108:109] op_sel_hi:[1,0]
	s_nop 0
	v_pk_fma_f32 v[44:45], v[86:87], v[24:25], v[100:101]
	v_pk_mul_f32 v[24:25], v[88:89], v[108:109] op_sel_hi:[1,0]
	s_nop 0
	v_pk_fma_f32 v[32:33], v[34:35], v[24:25], v[54:55]
	v_pk_mul_f32 v[24:25], v[94:95], v[108:109] op_sel_hi:[1,0]
	s_nop 0
	v_pk_fma_f32 v[48:49], v[52:53], v[24:25], v[102:103]
	v_pk_mul_f32 v[24:25], v[64:65], v[108:109] op_sel_hi:[1,0]
	s_nop 0
	v_pk_fma_f32 v[28:29], v[22:23], v[24:25], v[42:43]
	v_pk_mul_f32 v[22:23], v[96:97], v[108:109] op_sel_hi:[1,0]
	s_nop 0
	v_pk_fma_f32 v[40:41], v[20:21], v[22:23], v[40:41]
	v_pk_mul_f32 v[20:21], v[68:69], v[108:109] op_sel_hi:[1,0]
	v_pk_mul_f32 v[22:23], v[90:91], v[108:109] op_sel_hi:[1,0]
	v_pk_fma_f32 v[24:25], v[10:11], v[20:21], v[30:31]
	v_pk_mul_f32 v[10:11], v[98:99], v[108:109] op_sel_hi:[1,0]
	v_mov_b32_e32 v30, v16
	v_pk_fma_f32 v[10:11], v[8:9], v[10:11], v[92:93]
	v_pk_mul_f32 v[8:9], v[66:67], v[108:109] op_sel_hi:[1,0]
	v_mov_b32_e32 v31, v18
	v_pk_fma_f32 v[20:21], v[2:3], v[8:9], v[14:15]
	v_pk_mul_f32 v[2:3], v[72:73], v[108:109] op_sel_hi:[1,0]
	v_mov_b32_e32 v18, v17
	v_pk_fma_f32 v[0:1], v[0:1], v[2:3], v[12:13]
	v_pk_mul_f32 v[2:3], v[70:71], v[108:109] op_sel_hi:[1,0]
	s_nop 0
	v_pk_fma_f32 v[12:13], v[50:51], v[2:3], v[62:63]
	v_pk_mul_f32 v[2:3], v[76:77], v[108:109] op_sel_hi:[1,0]
	s_nop 0
	v_pk_fma_f32 v[36:37], v[60:61], v[2:3], v[104:105]
	v_pk_mul_f32 v[2:3], v[74:75], v[108:109] op_sel_hi:[1,0]
	s_nop 0
	v_pk_fma_f32 v[8:9], v[38:39], v[2:3], v[58:59]
	v_pk_mul_f32 v[2:3], v[82:83], v[108:109] op_sel_hi:[1,0]
	s_nop 0
	v_pk_fma_f32 v[14:15], v[56:57], v[2:3], v[106:107]
	v_pk_mul_f32 v[2:3], v[78:79], v[108:109] op_sel_hi:[1,0]
	s_nop 0
	v_pk_fma_f32 v[2:3], v[26:27], v[2:3], v[46:47]
	v_mov_b32_e32 v26, v4
	v_mov_b32_e32 v27, v6
	v_pk_fma_f32 v[34:35], v[26:27], v[22:23], v[30:31]
	v_pk_mul_f32 v[22:23], v[84:85], v[108:109] op_sel_hi:[1,0]
	v_mov_b32_e32 v6, v5
	v_pk_fma_f32 v[4:5], v[6:7], v[22:23], v[18:19]
	s_and_saveexec_b64 s[2:3], s[8:9]
	s_xor_b64 s[2:3], exec, s[2:3]
	s_cbranch_execz .LBB0_341
	s_andn2_b64 vcc, exec, s[4:5]
	s_cbranch_vccnz .LBB0_341
	v_lshl_add_u64 v[16:17], v[136:137], 2, v[128:129]
	v_mov_b32_e32 v18, v10
	v_mov_b32_e32 v19, v20
	v_mov_b32_e32 v20, v11
	v_mov_b32_e32 v10, v0
	v_mov_b32_e32 v11, v12
	v_mov_b32_e32 v12, v1
	v_mov_b32_e32 v0, v14
	v_mov_b32_e32 v1, v2
	v_mov_b32_e32 v2, v15
	v_mov_b32_e32 v30, v44
	v_mov_b32_e32 v31, v32
	v_mov_b32_e32 v32, v45
	v_mov_b32_e32 v26, v48
	v_mov_b32_e32 v27, v28
	v_mov_b32_e32 v28, v49
	v_mov_b32_e32 v22, v40
	v_mov_b32_e32 v23, v24
	v_mov_b32_e32 v24, v41
	v_mov_b32_e32 v6, v36
	v_mov_b32_e32 v7, v8
	v_mov_b32_e32 v8, v37
	global_store_dwordx4 v[16:17], v[0:3], off offset:96
	global_store_dwordx4 v[16:17], v[30:33], off
	global_store_dwordx4 v[16:17], v[26:29], off offset:16
	v_mov_b32_e32 v2, v34
	v_mov_b32_e32 v3, v4
	v_mov_b32_e32 v4, v35
	global_store_dwordx4 v[16:17], v[22:25], off offset:32
	global_store_dwordx4 v[16:17], v[18:21], off offset:48
	global_store_dwordx4 v[16:17], v[10:13], off offset:64
	global_store_dwordx4 v[16:17], v[6:9], off offset:80
	global_store_dwordx4 v[16:17], v[2:5], off offset:112
